# epiwide_sw: FFN_UP SwiGLU epilogue hand-written: 8 interleaved exp/rcp chains, row-pair exchange via v_permlane16_swap, 8 dwordx4 stores per thread (was 16 dwordx2)
# speedup vs baseline: 1.0218x; 1.0106x over previous
; #define PG8_STAGE(bufoff, gbase, voff) do { _Pragma("unroll") for (int _i = 0; _i < 2; ++_i) \
;         __builtin_amdgcn_global_load_lds((const unsigned*)((const char*)(gbase) + (voff)[_i]), (PG8_LAS unsigned*)(lds + (bufoff) + ldsw + _i * 8192), 16, 0, 0); } while (0)
; #define PG8_LDA(dst, b, h) do { _Pragma("unroll") for (int m = 0; m < 4; ++m) _Pragma("unroll") for (int k = 0; k < 2; ++k) dst[m][k] = *(const PG8_LAS bf16x8*)(lds + PG8_SA(b, h) + aoff + m * 2048 + k * 1024); } while (0)
; #define PG8_LDB(dst, b, h) do { _Pragma("unroll") for (int n = 0; n < 2; ++n) _Pragma("unroll") for (int k = 0; k < 2; ++k) dst[n][k] = *(const PG8_LAS bf16x8*)(lds + PG8_SB(b, h) + boff + n * 2048 + k * 1024); } while (0)
; #define PG8_MMA(ai, bj, At, Bt) do { __builtin_amdgcn_s_setprio(1); _Pragma("unroll") for (int m = 0; m < 4; ++m) _Pragma("unroll") for (int n = 0; n < 2; ++n) _Pragma("unroll") for (int k = 0; k < 2; ++k) \
;         acc[ai][bj][m][n] = __builtin_amdgcn_mfma_f32_16x16x32_bf16(Bt[n][k], At[m][k], acc[ai][bj][m][n], 0, 0, 0); __builtin_amdgcn_s_setprio(0); } while (0)
; #define PG8_WAIT_V(n) asm volatile("s_waitcnt vmcnt(" #n ")" ::: "memory")
; #define PG8_WAIT_L(n) asm volatile("s_waitcnt lgkmcnt(" #n ")" ::: "memory")
; template <class Epi>
; __device__ __forceinline__ void gemm_phase(PG8_LAS unsigned char* lds, const Gemm g, const Sched& S, const Epi& E) {
;     ...
;         for (int t = 0; t < nt; t += 2) {
;             const bool last = (t == nt - 2);
;             const char* a1 = cA + (size_t)(t + 1) * kstep;
;             const char* a2 = last ? nA : cA + (size_t)(t + 2) * kstep; const char* b2 = last ? nB : cB + (size_t)(t + 2) * kstep;
;             const char* a3 = a2 + kstep; const char* b3 = b2 + kstep;
;             PG8_LDB(B0, 0, 0); PG8_SCHED; PG8_LDA(At, 0, 0); PG8_STAGE(PG8_SA(1, 1), a1 + hsA, voffA);
;             PG8_WAIT_L(8); PG8_BAR; PG8_WAIT_L(0); PG8_MMA(0, 0, At, B0); PG8_BAR; PG8_SCHED;
;             PG8_LDB(B1, 0, 1); PG8_STAGE(PG8_SB(0, 0), b2, voffB);
;             PG8_BAR; PG8_WAIT_L(0); PG8_MMA(0, 1, At, B1); PG8_BAR;
;             PG8_LDA(At, 0, 1); PG8_STAGE(PG8_SA(0, 0), a2, voffA);
;             PG8_BAR; PG8_WAIT_L(0); PG8_MMA(1, 0, At, B0); PG8_BAR; PG8_SCHED;
;             PG8_STAGE(PG8_SB(0, 1), b2 + hsB, voffB);
;             PG8_WAIT_V(6); PG8_BAR; PG8_MMA(1, 1, At, B1); PG8_BAR;
.LBB0_908:
	s_add_u32 s8, s6, 0xfffc0080
	s_addc_u32 s9, s7, -1
	s_add_i32 s56, 0, 0x10000
	v_add_u32_e32 v145, s56, v135
	ds_read_b128 v[146:149], v145
	ds_read_b128 v[150:153], v145 offset:1024
	ds_read_b128 v[154:157], v145 offset:2048
	ds_read_b128 v[158:161], v145 offset:3072
	s_cmp_eq_u32 s55, 12
	s_cselect_b32 s11, s2, s9
	s_cselect_b32 s10, s3, s8
	s_cselect_b32 s9, s36, s49
	s_cselect_b32 s8, s37, s47
	v_lshl_add_u64 v[162:163], s[6:7], 0, v[130:131]
	s_add_i32 m0, s5, 0xc000
	ds_read_b128 v[178:181], v144
	ds_read_b128 v[182:185], v144 offset:1024
	ds_read_b128 v[186:189], v144 offset:2048
	ds_read_b128 v[190:193], v144 offset:3072
	ds_read_b128 v[194:197], v144 offset:4096
	ds_read_b128 v[198:201], v144 offset:5120
	ds_read_b128 v[202:205], v144 offset:6144
	ds_read_b128 v[206:209], v144 offset:7168
	global_load_lds_dwordx4 v[162:163], off
	v_lshl_add_u64 v[162:163], s[6:7], 0, v[132:133]
	s_add_i32 m0, s5, 0xe000
	s_nop 0
	global_load_lds_dwordx4 v[162:163], off
	s_waitcnt lgkmcnt(8)
	s_barrier
	s_waitcnt lgkmcnt(0)
	s_setprio 1
	s_waitcnt lgkmcnt(0)
	v_mfma_f32_16x16x32_bf16 v[124:127], v[146:149], v[178:181], v[124:127]
	v_mfma_f32_16x16x32_bf16 v[120:123], v[154:157], v[178:181], v[120:123]
	v_mfma_f32_16x16x32_bf16 v[108:111], v[146:149], v[186:189], v[108:111]
	v_mfma_f32_16x16x32_bf16 v[104:107], v[154:157], v[186:189], v[104:107]
	v_mfma_f32_16x16x32_bf16 v[92:95], v[146:149], v[194:197], v[92:95]
	v_mfma_f32_16x16x32_bf16 v[88:91], v[154:157], v[194:197], v[88:91]
	v_mfma_f32_16x16x32_bf16 v[76:79], v[146:149], v[202:205], v[76:79]
	v_mfma_f32_16x16x32_bf16 v[72:75], v[154:157], v[202:205], v[72:75]
	v_mfma_f32_16x16x32_bf16 v[124:127], v[150:153], v[182:185], v[124:127]
	v_mfma_f32_16x16x32_bf16 v[120:123], v[158:161], v[182:185], v[120:123]
	v_mfma_f32_16x16x32_bf16 v[108:111], v[150:153], v[190:193], v[108:111]
	v_mfma_f32_16x16x32_bf16 v[104:107], v[158:161], v[190:193], v[104:107]
	v_mfma_f32_16x16x32_bf16 v[92:95], v[150:153], v[198:201], v[92:95]
	v_mfma_f32_16x16x32_bf16 v[88:91], v[158:161], v[198:201], v[88:91]
	v_mfma_f32_16x16x32_bf16 v[76:79], v[150:153], v[206:209], v[76:79]
	v_mfma_f32_16x16x32_bf16 v[72:75], v[158:161], v[206:209], v[72:75]
	s_setprio 0
	s_barrier
	s_add_i32 s58, 0, 0x14000
	s_add_i32 s56, s56, s25
	v_add_u32_e32 v145, s58, v135
	v_lshl_add_u64 v[162:163], s[8:9], 0, v[166:167]
	s_mov_b32 m0, s56
	ds_read_b128 v[210:213], v145
	ds_read_b128 v[236:239], v145 offset:1024
	ds_read_b128 v[240:243], v145 offset:2048
	ds_read_b128 v[244:247], v145 offset:3072
	global_load_lds_dwordx4 v[162:163], off
	v_lshl_add_u64 v[172:173], s[8:9], 0, v[128:129]
	s_add_i32 m0, s56, 0x2000
	s_nop 0
	global_load_lds_dwordx4 v[172:173], off
	s_barrier
	s_waitcnt lgkmcnt(0)
	s_setprio 1
	s_waitcnt lgkmcnt(0)
	v_mfma_f32_16x16x32_bf16 v[116:119], v[210:213], v[178:181], v[116:119]
	v_mfma_f32_16x16x32_bf16 v[112:115], v[240:243], v[178:181], v[112:115]
	v_mfma_f32_16x16x32_bf16 v[100:103], v[210:213], v[186:189], v[100:103]
	v_mfma_f32_16x16x32_bf16 v[96:99], v[240:243], v[186:189], v[96:99]
	v_mfma_f32_16x16x32_bf16 v[84:87], v[210:213], v[194:197], v[84:87]
	v_mfma_f32_16x16x32_bf16 v[80:83], v[240:243], v[194:197], v[80:83]
	v_mfma_f32_16x16x32_bf16 v[68:71], v[210:213], v[202:205], v[68:71]
	v_mfma_f32_16x16x32_bf16 v[64:67], v[240:243], v[202:205], v[64:67]
	v_mfma_f32_16x16x32_bf16 v[116:119], v[236:239], v[182:185], v[116:119]
	v_mfma_f32_16x16x32_bf16 v[112:115], v[244:247], v[182:185], v[112:115]
	v_mfma_f32_16x16x32_bf16 v[100:103], v[236:239], v[190:193], v[100:103]
	v_mfma_f32_16x16x32_bf16 v[96:99], v[244:247], v[190:193], v[96:99]
	v_mfma_f32_16x16x32_bf16 v[84:87], v[236:239], v[198:201], v[84:87]
	v_mfma_f32_16x16x32_bf16 v[80:83], v[244:247], v[198:201], v[80:83]
	v_mfma_f32_16x16x32_bf16 v[68:71], v[236:239], v[206:209], v[68:71]
	v_mfma_f32_16x16x32_bf16 v[64:67], v[244:247], v[206:209], v[64:67]
	s_setprio 0
	s_mov_b32 m0, s5
	v_lshl_add_u64 v[174:175], s[10:11], 0, v[166:167]
	s_barrier
	ds_read_b128 v[178:181], v144 offset:16384
	ds_read_b128 v[182:185], v144 offset:17408
	ds_read_b128 v[186:189], v144 offset:18432
	ds_read_b128 v[190:193], v144 offset:19456
	ds_read_b128 v[194:197], v144 offset:20480
	ds_read_b128 v[198:201], v144 offset:21504
	ds_read_b128 v[202:205], v144 offset:22528
	ds_read_b128 v[206:209], v144 offset:23552
	global_load_lds_dwordx4 v[174:175], off
	v_lshl_add_u64 v[214:215], s[10:11], 0, v[128:129]
	s_mov_b32 m0, s26
	s_nop 0
	global_load_lds_dwordx4 v[214:215], off
	s_barrier
	s_waitcnt lgkmcnt(0)
	s_setprio 1
	s_waitcnt lgkmcnt(0)
	v_mfma_f32_16x16x32_bf16 v[60:63], v[146:149], v[178:181], v[60:63]
	v_mfma_f32_16x16x32_bf16 v[56:59], v[154:157], v[178:181], v[56:59]
	v_mfma_f32_16x16x32_bf16 v[44:47], v[146:149], v[186:189], v[44:47]
	v_mfma_f32_16x16x32_bf16 v[40:43], v[154:157], v[186:189], v[40:43]
	v_mfma_f32_16x16x32_bf16 v[28:31], v[146:149], v[194:197], v[28:31]
	v_mfma_f32_16x16x32_bf16 v[24:27], v[154:157], v[194:197], v[24:27]
	v_mfma_f32_16x16x32_bf16 v[12:15], v[146:149], v[202:205], v[12:15]
	v_mfma_f32_16x16x32_bf16 v[8:11], v[154:157], v[202:205], v[8:11]
	v_mfma_f32_16x16x32_bf16 v[60:63], v[150:153], v[182:185], v[60:63]
	v_mfma_f32_16x16x32_bf16 v[56:59], v[158:161], v[182:185], v[56:59]
	v_mfma_f32_16x16x32_bf16 v[44:47], v[150:153], v[190:193], v[44:47]
	v_mfma_f32_16x16x32_bf16 v[40:43], v[158:161], v[190:193], v[40:43]
	v_mfma_f32_16x16x32_bf16 v[28:31], v[150:153], v[198:201], v[28:31]
	v_mfma_f32_16x16x32_bf16 v[24:27], v[158:161], v[198:201], v[24:27]
	v_mfma_f32_16x16x32_bf16 v[12:15], v[150:153], v[206:209], v[12:15]
	v_mfma_f32_16x16x32_bf16 v[8:11], v[158:161], v[206:209], v[8:11]
	s_setprio 0
	s_barrier
; #define PG8_STAGE(bufoff, gbase, voff) do { _Pragma("unroll") for (int _i = 0; _i < 2; ++_i) \
;         __builtin_amdgcn_global_load_lds((const unsigned*)((const char*)(gbase) + (voff)[_i]), (PG8_LAS unsigned*)(lds + (bufoff) + ldsw + _i * 8192), 16, 0, 0); } while (0)
; #define PG8_LDA(dst, b, h) do { _Pragma("unroll") for (int m = 0; m < 4; ++m) _Pragma("unroll") for (int k = 0; k < 2; ++k) dst[m][k] = *(const PG8_LAS bf16x8*)(lds + PG8_SA(b, h) + aoff + m * 2048 + k * 1024); } while (0)
; #define PG8_LDB(dst, b, h) do { _Pragma("unroll") for (int n = 0; n < 2; ++n) _Pragma("unroll") for (int k = 0; k < 2; ++k) dst[n][k] = *(const PG8_LAS bf16x8*)(lds + PG8_SB(b, h) + boff + n * 2048 + k * 1024); } while (0)
; #define PG8_MMA(ai, bj, At, Bt) do { __builtin_amdgcn_s_setprio(1); _Pragma("unroll") for (int m = 0; m < 4; ++m) _Pragma("unroll") for (int n = 0; n < 2; ++n) _Pragma("unroll") for (int k = 0; k < 2; ++k) \
;         acc[ai][bj][m][n] = __builtin_amdgcn_mfma_f32_16x16x32_bf16(Bt[n][k], At[m][k], acc[ai][bj][m][n], 0, 0, 0); __builtin_amdgcn_s_setprio(0); } while (0)
; #define PG8_WAIT_V(n) asm volatile("s_waitcnt vmcnt(" #n ")" ::: "memory")
; #define PG8_WAIT_L(n) asm volatile("s_waitcnt lgkmcnt(" #n ")" ::: "memory")
; #define PG8_BAR __builtin_amdgcn_s_barrier()
; #define PG8_SCHED __builtin_amdgcn_sched_barrier(0)
; template <class Epi>
; __device__ __forceinline__ void gemm_phase(PG8_LAS unsigned char* lds, const Gemm g, const Sched& S, const Epi& E) {
;     ...
;             PG8_WAIT_V(6); PG8_BAR; PG8_MMA(1, 1, At, B1); PG8_BAR;
;             PG8_LDB(B0, 1, 0); PG8_SCHED; PG8_LDA(At, 1, 0); PG8_STAGE(PG8_SA(0, 1), a2 + hsA, voffA);
;             PG8_WAIT_L(8); PG8_BAR; PG8_WAIT_L(0); PG8_MMA(0, 0, At, B0); PG8_BAR; PG8_SCHED;
;             PG8_LDB(B1, 1, 1); PG8_STAGE(PG8_SB(1, 0), b3, voffB);
;             PG8_BAR; PG8_WAIT_L(0); PG8_MMA(0, 1, At, B1); PG8_BAR;
;             PG8_LDA(At, 1, 1); PG8_STAGE(PG8_SA(1, 0), a3, voffA);
;             PG8_BAR; PG8_WAIT_L(0); PG8_MMA(1, 0, At, B0); PG8_BAR; PG8_SCHED;
	s_add_u32 s56, s8, 0x40000
	s_addc_u32 s57, s9, 0
	s_add_i32 s58, s58, s25
	v_lshl_add_u64 v[146:147], s[56:57], 0, v[166:167]
	s_mov_b32 m0, s58
	s_nop 0
	global_load_lds_dwordx4 v[146:147], off
	v_lshl_add_u64 v[146:147], s[56:57], 0, v[128:129]
	s_add_i32 m0, s58, 0x2000
	s_nop 0
	global_load_lds_dwordx4 v[146:147], off
	s_waitcnt vmcnt(6)
	s_barrier
	s_setprio 1
	v_mfma_f32_16x16x32_bf16 v[52:55], v[210:213], v[178:181], v[52:55]
	v_mfma_f32_16x16x32_bf16 v[48:51], v[240:243], v[178:181], v[48:51]
	v_mfma_f32_16x16x32_bf16 v[36:39], v[210:213], v[186:189], v[36:39]
	v_mfma_f32_16x16x32_bf16 v[32:35], v[240:243], v[186:189], v[32:35]
	v_mfma_f32_16x16x32_bf16 v[20:23], v[210:213], v[194:197], v[20:23]
	v_mfma_f32_16x16x32_bf16 v[16:19], v[240:243], v[194:197], v[16:19]
	v_mfma_f32_16x16x32_bf16 v[4:7], v[210:213], v[202:205], v[4:7]
	v_mfma_f32_16x16x32_bf16 v[0:3], v[240:243], v[202:205], v[0:3]
	v_mfma_f32_16x16x32_bf16 v[52:55], v[236:239], v[182:185], v[52:55]
	v_mfma_f32_16x16x32_bf16 v[48:51], v[244:247], v[182:185], v[48:51]
	v_mfma_f32_16x16x32_bf16 v[36:39], v[236:239], v[190:193], v[36:39]
	v_mfma_f32_16x16x32_bf16 v[32:35], v[244:247], v[190:193], v[32:35]
	v_mfma_f32_16x16x32_bf16 v[20:23], v[236:239], v[198:201], v[20:23]
	v_mfma_f32_16x16x32_bf16 v[16:19], v[244:247], v[198:201], v[16:19]
	v_mfma_f32_16x16x32_bf16 v[4:7], v[236:239], v[206:209], v[4:7]
	v_mfma_f32_16x16x32_bf16 v[0:3], v[244:247], v[206:209], v[0:3]
	s_setprio 0
	s_add_i32 s56, 0, 0x18000
	v_add_u32_e32 v145, s56, v135
	s_barrier
	ds_read_b128 v[146:149], v145
	ds_read_b128 v[150:153], v145 offset:1024
	ds_read_b128 v[154:157], v145 offset:2048
	ds_read_b128 v[158:161], v145 offset:3072
	s_add_u32 s10, s10, 0x40000
	s_addc_u32 s11, s11, 0
	s_mov_b32 m0, s27
	v_lshl_add_u64 v[210:211], s[10:11], 0, v[166:167]
	ds_read_b128 v[178:181], v144 offset:32768
	ds_read_b128 v[182:185], v144 offset:33792
	ds_read_b128 v[186:189], v144 offset:34816
	ds_read_b128 v[190:193], v144 offset:35840
	ds_read_b128 v[194:197], v144 offset:36864
	ds_read_b128 v[198:201], v144 offset:37888
	ds_read_b128 v[202:205], v144 offset:38912
	ds_read_b128 v[206:209], v144 offset:39936
	global_load_lds_dwordx4 v[210:211], off
	v_lshl_add_u64 v[210:211], s[10:11], 0, v[128:129]
	s_mov_b32 m0, s38
	s_nop 0
	global_load_lds_dwordx4 v[210:211], off
	s_waitcnt lgkmcnt(8)
	s_barrier
	s_waitcnt lgkmcnt(0)
	s_setprio 1
	s_waitcnt lgkmcnt(0)
	v_mfma_f32_16x16x32_bf16 v[124:127], v[146:149], v[178:181], v[124:127]
	v_mfma_f32_16x16x32_bf16 v[120:123], v[154:157], v[178:181], v[120:123]
	v_mfma_f32_16x16x32_bf16 v[108:111], v[146:149], v[186:189], v[108:111]
	v_mfma_f32_16x16x32_bf16 v[104:107], v[154:157], v[186:189], v[104:107]
	v_mfma_f32_16x16x32_bf16 v[92:95], v[146:149], v[194:197], v[92:95]
	v_mfma_f32_16x16x32_bf16 v[88:91], v[154:157], v[194:197], v[88:91]
	v_mfma_f32_16x16x32_bf16 v[76:79], v[146:149], v[202:205], v[76:79]
	v_mfma_f32_16x16x32_bf16 v[72:75], v[154:157], v[202:205], v[72:75]
	v_mfma_f32_16x16x32_bf16 v[124:127], v[150:153], v[182:185], v[124:127]
	v_mfma_f32_16x16x32_bf16 v[120:123], v[158:161], v[182:185], v[120:123]
	v_mfma_f32_16x16x32_bf16 v[108:111], v[150:153], v[190:193], v[108:111]
	v_mfma_f32_16x16x32_bf16 v[104:107], v[158:161], v[190:193], v[104:107]
	v_mfma_f32_16x16x32_bf16 v[92:95], v[150:153], v[198:201], v[92:95]
	v_mfma_f32_16x16x32_bf16 v[88:91], v[158:161], v[198:201], v[88:91]
	v_mfma_f32_16x16x32_bf16 v[76:79], v[150:153], v[206:209], v[76:79]
	v_mfma_f32_16x16x32_bf16 v[72:75], v[158:161], v[206:209], v[72:75]
	s_setprio 0
	s_barrier
	s_add_i32 s10, 0, 0x1c000
	s_add_i32 s11, s56, s25
	v_add_u32_e32 v145, s10, v135
	v_lshl_add_u64 v[162:163], v[162:163], 0, s[76:77]
	s_mov_b32 m0, s11
	ds_read_b128 v[210:213], v145
	ds_read_b128 v[236:239], v145 offset:1024
	ds_read_b128 v[240:243], v145 offset:2048
	ds_read_b128 v[244:247], v145 offset:3072
	global_load_lds_dwordx4 v[162:163], off
	v_lshl_add_u64 v[162:163], v[172:173], 0, s[76:77]
	s_add_i32 m0, s11, 0x2000
	s_nop 0
	global_load_lds_dwordx4 v[162:163], off
	s_barrier
	s_waitcnt lgkmcnt(0)
	s_setprio 1
	s_waitcnt lgkmcnt(0)
	v_mfma_f32_16x16x32_bf16 v[116:119], v[210:213], v[178:181], v[116:119]
	v_mfma_f32_16x16x32_bf16 v[112:115], v[240:243], v[178:181], v[112:115]
	v_mfma_f32_16x16x32_bf16 v[100:103], v[210:213], v[186:189], v[100:103]
	v_mfma_f32_16x16x32_bf16 v[96:99], v[240:243], v[186:189], v[96:99]
	v_mfma_f32_16x16x32_bf16 v[84:87], v[210:213], v[194:197], v[84:87]
	v_mfma_f32_16x16x32_bf16 v[80:83], v[240:243], v[194:197], v[80:83]
	v_mfma_f32_16x16x32_bf16 v[68:71], v[210:213], v[202:205], v[68:71]
	v_mfma_f32_16x16x32_bf16 v[64:67], v[240:243], v[202:205], v[64:67]
	v_mfma_f32_16x16x32_bf16 v[116:119], v[236:239], v[182:185], v[116:119]
	v_mfma_f32_16x16x32_bf16 v[112:115], v[244:247], v[182:185], v[112:115]
	v_mfma_f32_16x16x32_bf16 v[100:103], v[236:239], v[190:193], v[100:103]
	v_mfma_f32_16x16x32_bf16 v[96:99], v[244:247], v[190:193], v[96:99]
	v_mfma_f32_16x16x32_bf16 v[84:87], v[236:239], v[198:201], v[84:87]
	v_mfma_f32_16x16x32_bf16 v[80:83], v[244:247], v[198:201], v[80:83]
	v_mfma_f32_16x16x32_bf16 v[68:71], v[236:239], v[206:209], v[68:71]
	v_mfma_f32_16x16x32_bf16 v[64:67], v[244:247], v[206:209], v[64:67]
	s_setprio 0
	s_mov_b32 m0, s39
	v_lshl_add_u64 v[162:163], v[174:175], 0, s[76:77]
	s_barrier
	ds_read_b128 v[178:181], v144 offset:49152
	ds_read_b128 v[182:185], v144 offset:50176
	ds_read_b128 v[186:189], v144 offset:51200
	ds_read_b128 v[190:193], v144 offset:52224
	ds_read_b128 v[194:197], v144 offset:53248
	ds_read_b128 v[198:201], v144 offset:54272
	ds_read_b128 v[202:205], v144 offset:55296
	ds_read_b128 v[206:209], v144 offset:56320
	global_load_lds_dwordx4 v[162:163], off
	v_lshl_add_u64 v[162:163], v[214:215], 0, s[76:77]
	s_mov_b32 m0, s54
	s_nop 0
	global_load_lds_dwordx4 v[162:163], off
	s_barrier
; __device__ __forceinline__ uint32_t pack2(float a, float b) { uint32_t r; asm("v_cvt_pk_bf16_f32 %0, %1, %2" : "=v"(r) : "v"(a), "v"(b)); return r; }
; __device__ __forceinline__ float siluf_(float x) { return x * __builtin_amdgcn_rcpf(1.0f + __expf(-x)); }
; #define PG8_STAGE(bufoff, gbase, voff) do { _Pragma("unroll") for (int _i = 0; _i < 2; ++_i) \
;         __builtin_amdgcn_global_load_lds((const unsigned*)((const char*)(gbase) + (voff)[_i]), (PG8_LAS unsigned*)(lds + (bufoff) + ldsw + _i * 8192), 16, 0, 0); } while (0)
; #define PG8_MMA(ai, bj, At, Bt) do { __builtin_amdgcn_s_setprio(1); _Pragma("unroll") for (int m = 0; m < 4; ++m) _Pragma("unroll") for (int n = 0; n < 2; ++n) _Pragma("unroll") for (int k = 0; k < 2; ++k) \
;         acc[ai][bj][m][n] = __builtin_amdgcn_mfma_f32_16x16x32_bf16(Bt[n][k], At[m][k], acc[ai][bj][m][n], 0, 0, 0); __builtin_amdgcn_s_setprio(0); } while (0)
; #define PG8_WAIT_V(n) asm volatile("s_waitcnt vmcnt(" #n ")" ::: "memory")
; #define PG8_WAIT_L(n) asm volatile("s_waitcnt lgkmcnt(" #n ")" ::: "memory")
; #define PG8_BAR __builtin_amdgcn_s_barrier()
; #define PG8_SCHED __builtin_amdgcn_sched_barrier(0)
; template <class Epi>
; __device__ __forceinline__ void gemm_phase(PG8_LAS unsigned char* lds, const Gemm g, const Sched& S, const Epi& E) {
;     ...
;             PG8_BAR; PG8_WAIT_L(0); PG8_MMA(1, 0, At, B0); PG8_BAR; PG8_SCHED;
;             PG8_STAGE(PG8_SB(1, 1), b3 + hsB, voffB);
;             PG8_WAIT_V(6); PG8_BAR; PG8_MMA(1, 1, At, B1); PG8_BAR;
;         }
;         E(acc, cur, wr, wc, fr, fq);
;   __device__ __forceinline__ void operator()(const f32x4 (&acc)[2][2][4][2], const pg8::Unit& u, int wr, int wc, int fr, int fq) const {
;     ...
;         if (kind == EPI_SWIGLU) {
; #pragma unroll
;           for (int bj = 0; bj < 2; ++bj) {
;             int hc = u.pn * 128 + bj * 64 + wc * 16 + fq * 4;
;             f32x4 g = acc[ai][bj][m][0], up = acc[ai][bj][m][1];
;             uint2 o; o.x = pack2(siluf_(g[0]) * up[0], siluf_(g[1]) * up[1]); o.y = pack2(siluf_(g[2]) * up[2], siluf_(g[3]) * up[3]);
;             *(uint2*)(outb + (size_t)row * ldo + hc) = o;
;           }
	s_waitcnt lgkmcnt(0)
	s_setprio 1
	s_waitcnt lgkmcnt(0)
	v_mfma_f32_16x16x32_bf16 v[60:63], v[146:149], v[178:181], v[60:63]
	v_mfma_f32_16x16x32_bf16 v[56:59], v[154:157], v[178:181], v[56:59]
	v_mfma_f32_16x16x32_bf16 v[44:47], v[146:149], v[186:189], v[44:47]
	v_mfma_f32_16x16x32_bf16 v[40:43], v[154:157], v[186:189], v[40:43]
	v_mfma_f32_16x16x32_bf16 v[28:31], v[146:149], v[194:197], v[28:31]
	v_mfma_f32_16x16x32_bf16 v[24:27], v[154:157], v[194:197], v[24:27]
	v_mfma_f32_16x16x32_bf16 v[12:15], v[146:149], v[202:205], v[12:15]
	v_mfma_f32_16x16x32_bf16 v[8:11], v[154:157], v[202:205], v[8:11]
	v_mfma_f32_16x16x32_bf16 v[60:63], v[150:153], v[182:185], v[60:63]
	v_mfma_f32_16x16x32_bf16 v[56:59], v[158:161], v[182:185], v[56:59]
	v_mfma_f32_16x16x32_bf16 v[44:47], v[150:153], v[190:193], v[44:47]
	v_mfma_f32_16x16x32_bf16 v[40:43], v[158:161], v[190:193], v[40:43]
	v_mfma_f32_16x16x32_bf16 v[28:31], v[150:153], v[198:201], v[28:31]
	v_mfma_f32_16x16x32_bf16 v[24:27], v[158:161], v[198:201], v[24:27]
	v_mfma_f32_16x16x32_bf16 v[12:15], v[150:153], v[206:209], v[12:15]
	v_mfma_f32_16x16x32_bf16 v[8:11], v[158:161], v[206:209], v[8:11]
	s_setprio 0
	s_barrier
	s_add_u32 s8, s8, 0x40080
	s_addc_u32 s9, s9, 0
	s_add_i32 s10, s10, s25
	v_lshl_add_u64 v[146:147], s[8:9], 0, v[166:167]
	s_mov_b32 m0, s10
	s_nop 0
	global_load_lds_dwordx4 v[146:147], off
	v_lshl_add_u64 v[146:147], s[8:9], 0, v[128:129]
	s_add_i32 m0, s10, 0x2000
	s_nop 0
	global_load_lds_dwordx4 v[146:147], off
	s_waitcnt vmcnt(6)
	s_barrier
	s_setprio 1
	v_mfma_f32_16x16x32_bf16 v[52:55], v[210:213], v[178:181], v[52:55]
	v_mfma_f32_16x16x32_bf16 v[48:51], v[240:243], v[178:181], v[48:51]
	v_mfma_f32_16x16x32_bf16 v[36:39], v[210:213], v[186:189], v[36:39]
	v_mfma_f32_16x16x32_bf16 v[32:35], v[240:243], v[186:189], v[32:35]
	v_mfma_f32_16x16x32_bf16 v[20:23], v[210:213], v[194:197], v[20:23]
	v_mfma_f32_16x16x32_bf16 v[16:19], v[240:243], v[194:197], v[16:19]
	v_mfma_f32_16x16x32_bf16 v[4:7], v[210:213], v[202:205], v[4:7]
	v_mfma_f32_16x16x32_bf16 v[0:3], v[240:243], v[202:205], v[0:3]
	v_mfma_f32_16x16x32_bf16 v[52:55], v[236:239], v[182:185], v[52:55]
	v_mfma_f32_16x16x32_bf16 v[48:51], v[244:247], v[182:185], v[48:51]
	v_mfma_f32_16x16x32_bf16 v[36:39], v[236:239], v[190:193], v[36:39]
	v_mfma_f32_16x16x32_bf16 v[32:35], v[244:247], v[190:193], v[32:35]
	v_mfma_f32_16x16x32_bf16 v[20:23], v[236:239], v[198:201], v[20:23]
	v_mfma_f32_16x16x32_bf16 v[16:19], v[244:247], v[198:201], v[16:19]
	v_mfma_f32_16x16x32_bf16 v[4:7], v[236:239], v[206:209], v[4:7]
	v_mfma_f32_16x16x32_bf16 v[0:3], v[244:247], v[206:209], v[0:3]
	s_setprio 0
	s_add_i32 s55, s55, 2
	s_add_u32 s6, s6, 0x100
	s_addc_u32 s7, s7, 0
	s_add_u32 s47, s47, 0x100
	s_addc_u32 s49, s49, 0
	s_cmp_gt_u32 s55, 13
	s_barrier
	s_cbranch_scc0 .LBB0_908
	s_lshl_b32 s2, s4, 8
	s_movk_i32 s3, 0x1600
	s_movk_i32 s84, 0x1600
	v_bfe_u32 v158, v231, 4, 1
	v_mul_u32_u24_e32 v158, 0x15ff8, v158
	v_lshl_or_b32 v159, s29, 7, v136
	v_lshl_add_u32 v194, v159, 1, v158
	v_mov_b32_e32 v195, 0
	v_add_u32_e32 v178, s2, v134
	v_mul_u32_u24_e32 v178, 0x1600, v178
	v_mov_b32_e32 v179, 0
	v_lshl_add_u64 v[178:179], s[44:45], 0, v[178:179]
	v_lshl_add_u64 v[178:179], v[178:179], 0, v[194:195]
	v_add_u32_e32 v180, s2, v138
	v_mul_u32_u24_e32 v180, 0x1600, v180
	v_mov_b32_e32 v181, 0
	v_lshl_add_u64 v[180:181], s[44:45], 0, v[180:181]
	v_lshl_add_u64 v[180:181], v[180:181], 0, v[194:195]
	v_add_u32_e32 v182, s2, v140
	v_mul_u32_u24_e32 v182, 0x1600, v182
	v_mov_b32_e32 v183, 0
	v_lshl_add_u64 v[182:183], s[44:45], 0, v[182:183]
	v_lshl_add_u64 v[182:183], v[182:183], 0, v[194:195]
	v_add_u32_e32 v184, s2, v142
	v_mul_u32_u24_e32 v184, 0x1600, v184
	v_mov_b32_e32 v185, 0
	v_lshl_add_u64 v[184:185], s[44:45], 0, v[184:185]
	v_lshl_add_u64 v[184:185], v[184:185], 0, v[194:195]
	s_and_b64 vcc, exec, s[40:41]
	s_mov_b32 s29, s46
	s_mov_b32 s4, s48
	s_mov_b64 s[8:9], s[52:53]
	s_mov_b64 s[6:7], s[50:51]
	v_mul_f32_e32 v186, 0xbfb8aa3b, v124
	v_mul_f32_e32 v187, 0xbfb8aa3b, v125
	v_mul_f32_e32 v188, 0xbfb8aa3b, v126
	v_mul_f32_e32 v189, 0xbfb8aa3b, v127
	v_mul_f32_e32 v190, 0xbfb8aa3b, v108
	v_mul_f32_e32 v191, 0xbfb8aa3b, v109
	v_mul_f32_e32 v192, 0xbfb8aa3b, v110
	v_mul_f32_e32 v193, 0xbfb8aa3b, v111
	v_exp_f32_e32 v186, v186
	v_exp_f32_e32 v187, v187
	v_exp_f32_e32 v188, v188
	v_exp_f32_e32 v189, v189
	v_exp_f32_e32 v190, v190
	v_exp_f32_e32 v191, v191
	v_exp_f32_e32 v192, v192
	v_exp_f32_e32 v193, v193
	v_add_f32_e32 v186, 1.0, v186
	v_add_f32_e32 v187, 1.0, v187
	v_add_f32_e32 v188, 1.0, v188
	v_add_f32_e32 v189, 1.0, v189
	v_add_f32_e32 v190, 1.0, v190
	v_add_f32_e32 v191, 1.0, v191
	v_add_f32_e32 v192, 1.0, v192
	v_add_f32_e32 v193, 1.0, v193
	v_rcp_f32_e32 v186, v186
	v_rcp_f32_e32 v187, v187
	v_rcp_f32_e32 v188, v188
	v_rcp_f32_e32 v189, v189
	v_rcp_f32_e32 v190, v190
	v_rcp_f32_e32 v191, v191
	v_rcp_f32_e32 v192, v192
	v_rcp_f32_e32 v193, v193
	v_mul_f32_e32 v186, v124, v186
	v_mul_f32_e32 v187, v125, v187
	v_mul_f32_e32 v188, v126, v188
	v_mul_f32_e32 v189, v127, v189
	v_mul_f32_e32 v190, v108, v190
	v_mul_f32_e32 v191, v109, v191
	v_mul_f32_e32 v192, v110, v192
	v_mul_f32_e32 v193, v111, v193
	v_mul_f32_e32 v186, v120, v186
	v_mul_f32_e32 v187, v121, v187
	v_mul_f32_e32 v188, v122, v188
	v_mul_f32_e32 v189, v123, v189
	v_mul_f32_e32 v190, v104, v190
	v_mul_f32_e32 v191, v105, v191
	v_mul_f32_e32 v192, v106, v192
	v_mul_f32_e32 v193, v107, v193
	v_cvt_pk_bf16_f32 v196, v186, v187
	v_cvt_pk_bf16_f32 v197, v188, v189
	v_cvt_pk_bf16_f32 v198, v190, v191
	v_cvt_pk_bf16_f32 v199, v192, v193
	s_nop 1
	v_permlane16_swap_b32_e32 v196, v198
; __device__ __forceinline__ uint32_t pack2(float a, float b) { uint32_t r; asm("v_cvt_pk_bf16_f32 %0, %1, %2" : "=v"(r) : "v"(a), "v"(b)); return r; }
; __device__ __forceinline__ float siluf_(float x) { return x * __builtin_amdgcn_rcpf(1.0f + __expf(-x)); }
;   __device__ __forceinline__ void operator()(const f32x4 (&acc)[2][2][4][2], const pg8::Unit& u, int wr, int wc, int fr, int fq) const {
;     ...
;         if (kind == EPI_SWIGLU) {
; #pragma unroll
;           for (int bj = 0; bj < 2; ++bj) {
;             int hc = u.pn * 128 + bj * 64 + wc * 16 + fq * 4;
;             f32x4 g = acc[ai][bj][m][0], up = acc[ai][bj][m][1];
;             uint2 o; o.x = pack2(siluf_(g[0]) * up[0], siluf_(g[1]) * up[1]); o.y = pack2(siluf_(g[2]) * up[2], siluf_(g[3]) * up[3]);
;             *(uint2*)(outb + (size_t)row * ldo + hc) = o;
;           }
	v_permlane16_swap_b32_e32 v197, v199
	global_store_dwordx4 v[178:179], v[196:199], off
	v_mul_f32_e32 v186, 0xbfb8aa3b, v116
	v_mul_f32_e32 v187, 0xbfb8aa3b, v117
	v_mul_f32_e32 v188, 0xbfb8aa3b, v118
	v_mul_f32_e32 v189, 0xbfb8aa3b, v119
	v_mul_f32_e32 v190, 0xbfb8aa3b, v100
	v_mul_f32_e32 v191, 0xbfb8aa3b, v101
	v_mul_f32_e32 v192, 0xbfb8aa3b, v102
	v_mul_f32_e32 v193, 0xbfb8aa3b, v103
	v_exp_f32_e32 v186, v186
	v_exp_f32_e32 v187, v187
	v_exp_f32_e32 v188, v188
	v_exp_f32_e32 v189, v189
	v_exp_f32_e32 v190, v190
	v_exp_f32_e32 v191, v191
	v_exp_f32_e32 v192, v192
	v_exp_f32_e32 v193, v193
	v_add_f32_e32 v186, 1.0, v186
	v_add_f32_e32 v187, 1.0, v187
	v_add_f32_e32 v188, 1.0, v188
	v_add_f32_e32 v189, 1.0, v189
	v_add_f32_e32 v190, 1.0, v190
	v_add_f32_e32 v191, 1.0, v191
	v_add_f32_e32 v192, 1.0, v192
	v_add_f32_e32 v193, 1.0, v193
	v_rcp_f32_e32 v186, v186
	v_rcp_f32_e32 v187, v187
	v_rcp_f32_e32 v188, v188
	v_rcp_f32_e32 v189, v189
	v_rcp_f32_e32 v190, v190
	v_rcp_f32_e32 v191, v191
	v_rcp_f32_e32 v192, v192
	v_rcp_f32_e32 v193, v193
	v_mul_f32_e32 v186, v116, v186
	v_mul_f32_e32 v187, v117, v187
	v_mul_f32_e32 v188, v118, v188
	v_mul_f32_e32 v189, v119, v189
	v_mul_f32_e32 v190, v100, v190
	v_mul_f32_e32 v191, v101, v191
	v_mul_f32_e32 v192, v102, v192
	v_mul_f32_e32 v193, v103, v193
	v_mul_f32_e32 v186, v112, v186
	v_mul_f32_e32 v187, v113, v187
	v_mul_f32_e32 v188, v114, v188
	v_mul_f32_e32 v189, v115, v189
	v_mul_f32_e32 v190, v96, v190
	v_mul_f32_e32 v191, v97, v191
	v_mul_f32_e32 v192, v98, v192
	v_mul_f32_e32 v193, v99, v193
	v_cvt_pk_bf16_f32 v200, v186, v187
	v_cvt_pk_bf16_f32 v201, v188, v189
	v_cvt_pk_bf16_f32 v202, v190, v191
	v_cvt_pk_bf16_f32 v203, v192, v193
	s_nop 1
	v_permlane16_swap_b32_e32 v200, v202
	v_permlane16_swap_b32_e32 v201, v203
	global_store_dwordx4 v[178:179], v[200:203], off offset:128
	v_mul_f32_e32 v186, 0xbfb8aa3b, v92
	v_mul_f32_e32 v187, 0xbfb8aa3b, v93
	v_mul_f32_e32 v188, 0xbfb8aa3b, v94
	v_mul_f32_e32 v189, 0xbfb8aa3b, v95
	v_mul_f32_e32 v190, 0xbfb8aa3b, v76
	v_mul_f32_e32 v191, 0xbfb8aa3b, v77
	v_mul_f32_e32 v192, 0xbfb8aa3b, v78
	v_mul_f32_e32 v193, 0xbfb8aa3b, v79
	v_exp_f32_e32 v186, v186
	v_exp_f32_e32 v187, v187
	v_exp_f32_e32 v188, v188
	v_exp_f32_e32 v189, v189
	v_exp_f32_e32 v190, v190
	v_exp_f32_e32 v191, v191
	v_exp_f32_e32 v192, v192
	v_exp_f32_e32 v193, v193
	v_add_f32_e32 v186, 1.0, v186
	v_add_f32_e32 v187, 1.0, v187
	v_add_f32_e32 v188, 1.0, v188
	v_add_f32_e32 v189, 1.0, v189
	v_add_f32_e32 v190, 1.0, v190
	v_add_f32_e32 v191, 1.0, v191
	v_add_f32_e32 v192, 1.0, v192
	v_add_f32_e32 v193, 1.0, v193
	v_rcp_f32_e32 v186, v186
	v_rcp_f32_e32 v187, v187
	v_rcp_f32_e32 v188, v188
	v_rcp_f32_e32 v189, v189
	v_rcp_f32_e32 v190, v190
	v_rcp_f32_e32 v191, v191
	v_rcp_f32_e32 v192, v192
	v_rcp_f32_e32 v193, v193
	v_mul_f32_e32 v186, v92, v186
	v_mul_f32_e32 v187, v93, v187
	v_mul_f32_e32 v188, v94, v188
	v_mul_f32_e32 v189, v95, v189
	v_mul_f32_e32 v190, v76, v190
	v_mul_f32_e32 v191, v77, v191
	v_mul_f32_e32 v192, v78, v192
	v_mul_f32_e32 v193, v79, v193
	v_mul_f32_e32 v186, v88, v186
	v_mul_f32_e32 v187, v89, v187
	v_mul_f32_e32 v188, v90, v188
	v_mul_f32_e32 v189, v91, v189
	v_mul_f32_e32 v190, v72, v190
	v_mul_f32_e32 v191, v73, v191
	v_mul_f32_e32 v192, v74, v192
	v_mul_f32_e32 v193, v75, v193
	v_cvt_pk_bf16_f32 v150, v186, v187
	v_cvt_pk_bf16_f32 v151, v188, v189
	v_cvt_pk_bf16_f32 v152, v190, v191
	v_cvt_pk_bf16_f32 v153, v192, v193
	s_nop 1
	v_permlane16_swap_b32_e32 v150, v152
	v_permlane16_swap_b32_e32 v151, v153
	global_store_dwordx4 v[180:181], v[150:153], off
	v_mul_f32_e32 v186, 0xbfb8aa3b, v84
	v_mul_f32_e32 v187, 0xbfb8aa3b, v85
	v_mul_f32_e32 v188, 0xbfb8aa3b, v86
	v_mul_f32_e32 v189, 0xbfb8aa3b, v87
	v_mul_f32_e32 v190, 0xbfb8aa3b, v68
	v_mul_f32_e32 v191, 0xbfb8aa3b, v69
	v_mul_f32_e32 v192, 0xbfb8aa3b, v70
	v_mul_f32_e32 v193, 0xbfb8aa3b, v71
	v_exp_f32_e32 v186, v186
	v_exp_f32_e32 v187, v187
	v_exp_f32_e32 v188, v188
	v_exp_f32_e32 v189, v189
	v_exp_f32_e32 v190, v190
	v_exp_f32_e32 v191, v191
	v_exp_f32_e32 v192, v192
	v_exp_f32_e32 v193, v193
	v_add_f32_e32 v186, 1.0, v186
	v_add_f32_e32 v187, 1.0, v187
	v_add_f32_e32 v188, 1.0, v188
	v_add_f32_e32 v189, 1.0, v189
	v_add_f32_e32 v190, 1.0, v190
	v_add_f32_e32 v191, 1.0, v191
	v_add_f32_e32 v192, 1.0, v192
	v_add_f32_e32 v193, 1.0, v193
	v_rcp_f32_e32 v186, v186
	v_rcp_f32_e32 v187, v187
	v_rcp_f32_e32 v188, v188
	v_rcp_f32_e32 v189, v189
	v_rcp_f32_e32 v190, v190
	v_rcp_f32_e32 v191, v191
	v_rcp_f32_e32 v192, v192
	v_rcp_f32_e32 v193, v193
	v_mul_f32_e32 v186, v84, v186
	v_mul_f32_e32 v187, v85, v187
	v_mul_f32_e32 v188, v86, v188
	v_mul_f32_e32 v189, v87, v189
	v_mul_f32_e32 v190, v68, v190
	v_mul_f32_e32 v191, v69, v191
	v_mul_f32_e32 v192, v70, v192
	v_mul_f32_e32 v193, v71, v193
	v_mul_f32_e32 v186, v80, v186
	v_mul_f32_e32 v187, v81, v187
	v_mul_f32_e32 v188, v82, v188
	v_mul_f32_e32 v189, v83, v189
	v_mul_f32_e32 v190, v64, v190
	v_mul_f32_e32 v191, v65, v191
	v_mul_f32_e32 v192, v66, v192
	v_mul_f32_e32 v193, v67, v193
	v_cvt_pk_bf16_f32 v154, v186, v187
	v_cvt_pk_bf16_f32 v155, v188, v189
	v_cvt_pk_bf16_f32 v156, v190, v191
	v_cvt_pk_bf16_f32 v157, v192, v193
	s_nop 1
	v_permlane16_swap_b32_e32 v154, v156
	v_permlane16_swap_b32_e32 v155, v157
	global_store_dwordx4 v[180:181], v[154:157], off offset:128
	v_mul_f32_e32 v186, 0xbfb8aa3b, v60
	v_mul_f32_e32 v187, 0xbfb8aa3b, v61
	v_mul_f32_e32 v188, 0xbfb8aa3b, v62
	v_mul_f32_e32 v189, 0xbfb8aa3b, v63
	v_mul_f32_e32 v190, 0xbfb8aa3b, v44
	v_mul_f32_e32 v191, 0xbfb8aa3b, v45
	v_mul_f32_e32 v192, 0xbfb8aa3b, v46
	v_mul_f32_e32 v193, 0xbfb8aa3b, v47
; __device__ __forceinline__ uint32_t pack2(float a, float b) { uint32_t r; asm("v_cvt_pk_bf16_f32 %0, %1, %2" : "=v"(r) : "v"(a), "v"(b)); return r; }
; __device__ __forceinline__ float siluf_(float x) { return x * __builtin_amdgcn_rcpf(1.0f + __expf(-x)); }
; #define PG8_WAIT_V(n) asm volatile("s_waitcnt vmcnt(" #n ")" ::: "memory")
; #define PG8_BAR __builtin_amdgcn_s_barrier()
; template <class Epi>
; __device__ __forceinline__ void gemm_phase(PG8_LAS unsigned char* lds, const Gemm g, const Sched& S, const Epi& E) {
;     ...
;         E(acc, cur, wr, wc, fr, fq);
;         if (!has_next) break;
; #pragma unroll
;         for (int a = 0; a < 2; ++a)
; #pragma unroll
;             for (int b = 0; b < 2; ++b)
; #pragma unroll
;                 for (int m = 0; m < 4; ++m)
; #pragma unroll
;                     for (int n = 0; n < 2; ++n) acc[a][b][m][n] = (f32x4){0.f, 0.f, 0.f, 0.f};
;         cur = nxt; cA = nA; cB = nB; ++ui;
;     }
;     PG8_WAIT_V(0);
;     if (wr == 0) PG8_BAR;
;     PG8_BAR;
;   __device__ __forceinline__ void operator()(const f32x4 (&acc)[2][2][4][2], const pg8::Unit& u, int wr, int wc, int fr, int fq) const {
;     ...
;         if (kind == EPI_SWIGLU) {
; #pragma unroll
;           for (int bj = 0; bj < 2; ++bj) {
;             int hc = u.pn * 128 + bj * 64 + wc * 16 + fq * 4;
;             f32x4 g = acc[ai][bj][m][0], up = acc[ai][bj][m][1];
;             uint2 o; o.x = pack2(siluf_(g[0]) * up[0], siluf_(g[1]) * up[1]); o.y = pack2(siluf_(g[2]) * up[2], siluf_(g[3]) * up[3]);
;             *(uint2*)(outb + (size_t)row * ldo + hc) = o;
;           }
	v_exp_f32_e32 v186, v186
	v_exp_f32_e32 v187, v187
	v_exp_f32_e32 v188, v188
	v_exp_f32_e32 v189, v189
	v_exp_f32_e32 v190, v190
	v_exp_f32_e32 v191, v191
	v_exp_f32_e32 v192, v192
	v_exp_f32_e32 v193, v193
	v_add_f32_e32 v186, 1.0, v186
	v_add_f32_e32 v187, 1.0, v187
	v_add_f32_e32 v188, 1.0, v188
	v_add_f32_e32 v189, 1.0, v189
	v_add_f32_e32 v190, 1.0, v190
	v_add_f32_e32 v191, 1.0, v191
	v_add_f32_e32 v192, 1.0, v192
	v_add_f32_e32 v193, 1.0, v193
	v_rcp_f32_e32 v186, v186
	v_rcp_f32_e32 v187, v187
	v_rcp_f32_e32 v188, v188
	v_rcp_f32_e32 v189, v189
	v_rcp_f32_e32 v190, v190
	v_rcp_f32_e32 v191, v191
	v_rcp_f32_e32 v192, v192
	v_rcp_f32_e32 v193, v193
	v_mul_f32_e32 v186, v60, v186
	v_mul_f32_e32 v187, v61, v187
	v_mul_f32_e32 v188, v62, v188
	v_mul_f32_e32 v189, v63, v189
	v_mul_f32_e32 v190, v44, v190
	v_mul_f32_e32 v191, v45, v191
	v_mul_f32_e32 v192, v46, v192
	v_mul_f32_e32 v193, v47, v193
	v_mul_f32_e32 v186, v56, v186
	v_mul_f32_e32 v187, v57, v187
	v_mul_f32_e32 v188, v58, v188
	v_mul_f32_e32 v189, v59, v189
	v_mul_f32_e32 v190, v40, v190
	v_mul_f32_e32 v191, v41, v191
	v_mul_f32_e32 v192, v42, v192
	v_mul_f32_e32 v193, v43, v193
	v_cvt_pk_bf16_f32 v196, v186, v187
	v_cvt_pk_bf16_f32 v197, v188, v189
	v_cvt_pk_bf16_f32 v198, v190, v191
	v_cvt_pk_bf16_f32 v199, v192, v193
	s_nop 1
	v_permlane16_swap_b32_e32 v196, v198
	v_permlane16_swap_b32_e32 v197, v199
	global_store_dwordx4 v[182:183], v[196:199], off
	v_mul_f32_e32 v186, 0xbfb8aa3b, v52
	v_mul_f32_e32 v187, 0xbfb8aa3b, v53
	v_mul_f32_e32 v188, 0xbfb8aa3b, v54
	v_mul_f32_e32 v189, 0xbfb8aa3b, v55
	v_mul_f32_e32 v190, 0xbfb8aa3b, v36
	v_mul_f32_e32 v191, 0xbfb8aa3b, v37
	v_mul_f32_e32 v192, 0xbfb8aa3b, v38
	v_mul_f32_e32 v193, 0xbfb8aa3b, v39
	v_exp_f32_e32 v186, v186
	v_exp_f32_e32 v187, v187
	v_exp_f32_e32 v188, v188
	v_exp_f32_e32 v189, v189
	v_exp_f32_e32 v190, v190
	v_exp_f32_e32 v191, v191
	v_exp_f32_e32 v192, v192
	v_exp_f32_e32 v193, v193
	v_add_f32_e32 v186, 1.0, v186
	v_add_f32_e32 v187, 1.0, v187
	v_add_f32_e32 v188, 1.0, v188
	v_add_f32_e32 v189, 1.0, v189
	v_add_f32_e32 v190, 1.0, v190
	v_add_f32_e32 v191, 1.0, v191
	v_add_f32_e32 v192, 1.0, v192
	v_add_f32_e32 v193, 1.0, v193
	v_rcp_f32_e32 v186, v186
	v_rcp_f32_e32 v187, v187
	v_rcp_f32_e32 v188, v188
	v_rcp_f32_e32 v189, v189
	v_rcp_f32_e32 v190, v190
	v_rcp_f32_e32 v191, v191
	v_rcp_f32_e32 v192, v192
	v_rcp_f32_e32 v193, v193
	v_mul_f32_e32 v186, v52, v186
	v_mul_f32_e32 v187, v53, v187
	v_mul_f32_e32 v188, v54, v188
	v_mul_f32_e32 v189, v55, v189
	v_mul_f32_e32 v190, v36, v190
	v_mul_f32_e32 v191, v37, v191
	v_mul_f32_e32 v192, v38, v192
	v_mul_f32_e32 v193, v39, v193
	v_mul_f32_e32 v186, v48, v186
	v_mul_f32_e32 v187, v49, v187
	v_mul_f32_e32 v188, v50, v188
	v_mul_f32_e32 v189, v51, v189
	v_mul_f32_e32 v190, v32, v190
	v_mul_f32_e32 v191, v33, v191
	v_mul_f32_e32 v192, v34, v192
	v_mul_f32_e32 v193, v35, v193
	v_cvt_pk_bf16_f32 v200, v186, v187
	v_cvt_pk_bf16_f32 v201, v188, v189
	v_cvt_pk_bf16_f32 v202, v190, v191
	v_cvt_pk_bf16_f32 v203, v192, v193
	s_nop 1
	v_permlane16_swap_b32_e32 v200, v202
	v_permlane16_swap_b32_e32 v201, v203
	global_store_dwordx4 v[182:183], v[200:203], off offset:128
	v_mul_f32_e32 v186, 0xbfb8aa3b, v28
	v_mul_f32_e32 v187, 0xbfb8aa3b, v29
	v_mul_f32_e32 v188, 0xbfb8aa3b, v30
	v_mul_f32_e32 v189, 0xbfb8aa3b, v31
	v_mul_f32_e32 v190, 0xbfb8aa3b, v12
	v_mul_f32_e32 v191, 0xbfb8aa3b, v13
	v_mul_f32_e32 v192, 0xbfb8aa3b, v14
	v_mul_f32_e32 v193, 0xbfb8aa3b, v15
	v_exp_f32_e32 v186, v186
	v_exp_f32_e32 v187, v187
	v_exp_f32_e32 v188, v188
	v_exp_f32_e32 v189, v189
	v_exp_f32_e32 v190, v190
	v_exp_f32_e32 v191, v191
	v_exp_f32_e32 v192, v192
	v_exp_f32_e32 v193, v193
	v_add_f32_e32 v186, 1.0, v186
	v_add_f32_e32 v187, 1.0, v187
	v_add_f32_e32 v188, 1.0, v188
	v_add_f32_e32 v189, 1.0, v189
	v_add_f32_e32 v190, 1.0, v190
	v_add_f32_e32 v191, 1.0, v191
	v_add_f32_e32 v192, 1.0, v192
	v_add_f32_e32 v193, 1.0, v193
	v_rcp_f32_e32 v186, v186
	v_rcp_f32_e32 v187, v187
	v_rcp_f32_e32 v188, v188
	v_rcp_f32_e32 v189, v189
	v_rcp_f32_e32 v190, v190
	v_rcp_f32_e32 v191, v191
	v_rcp_f32_e32 v192, v192
	v_rcp_f32_e32 v193, v193
	v_mul_f32_e32 v186, v28, v186
	v_mul_f32_e32 v187, v29, v187
	v_mul_f32_e32 v188, v30, v188
	v_mul_f32_e32 v189, v31, v189
	v_mul_f32_e32 v190, v12, v190
	v_mul_f32_e32 v191, v13, v191
	v_mul_f32_e32 v192, v14, v192
	v_mul_f32_e32 v193, v15, v193
	v_mul_f32_e32 v186, v24, v186
	v_mul_f32_e32 v187, v25, v187
	v_mul_f32_e32 v188, v26, v188
	v_mul_f32_e32 v189, v27, v189
	v_mul_f32_e32 v190, v8, v190
	v_mul_f32_e32 v191, v9, v191
	v_mul_f32_e32 v192, v10, v192
	v_mul_f32_e32 v193, v11, v193
	v_cvt_pk_bf16_f32 v150, v186, v187
	v_cvt_pk_bf16_f32 v151, v188, v189
	v_cvt_pk_bf16_f32 v152, v190, v191
	v_cvt_pk_bf16_f32 v153, v192, v193
	s_nop 1
	v_permlane16_swap_b32_e32 v150, v152
	v_permlane16_swap_b32_e32 v151, v153
	global_store_dwordx4 v[184:185], v[150:153], off
	v_mul_f32_e32 v186, 0xbfb8aa3b, v20
	v_mul_f32_e32 v187, 0xbfb8aa3b, v21
	v_mul_f32_e32 v188, 0xbfb8aa3b, v22
	v_mul_f32_e32 v189, 0xbfb8aa3b, v23
	v_mul_f32_e32 v190, 0xbfb8aa3b, v4
	v_mul_f32_e32 v191, 0xbfb8aa3b, v5
	v_mul_f32_e32 v192, 0xbfb8aa3b, v6
	v_mul_f32_e32 v193, 0xbfb8aa3b, v7
	v_exp_f32_e32 v186, v186
	v_exp_f32_e32 v187, v187
	v_exp_f32_e32 v188, v188
	v_exp_f32_e32 v189, v189
	v_exp_f32_e32 v190, v190
	v_exp_f32_e32 v191, v191
	v_exp_f32_e32 v192, v192
	v_exp_f32_e32 v193, v193
	v_add_f32_e32 v186, 1.0, v186
	v_add_f32_e32 v187, 1.0, v187
	v_add_f32_e32 v188, 1.0, v188
	v_add_f32_e32 v189, 1.0, v189
	v_add_f32_e32 v190, 1.0, v190
	v_add_f32_e32 v191, 1.0, v191
	v_add_f32_e32 v192, 1.0, v192
	v_add_f32_e32 v193, 1.0, v193
	v_rcp_f32_e32 v186, v186
	v_rcp_f32_e32 v187, v187
	v_rcp_f32_e32 v188, v188
	v_rcp_f32_e32 v189, v189
	v_rcp_f32_e32 v190, v190
	v_rcp_f32_e32 v191, v191
	v_rcp_f32_e32 v192, v192
	v_rcp_f32_e32 v193, v193
	v_mul_f32_e32 v186, v20, v186
	v_mul_f32_e32 v187, v21, v187
	v_mul_f32_e32 v188, v22, v188
	v_mul_f32_e32 v189, v23, v189
	v_mul_f32_e32 v190, v4, v190
	v_mul_f32_e32 v191, v5, v191
	v_mul_f32_e32 v192, v6, v192
	v_mul_f32_e32 v193, v7, v193
	v_mul_f32_e32 v186, v16, v186
	v_mul_f32_e32 v187, v17, v187
	v_mul_f32_e32 v188, v18, v188
	v_mul_f32_e32 v189, v19, v189
	v_mul_f32_e32 v190, v0, v190
	v_mul_f32_e32 v191, v1, v191
	v_mul_f32_e32 v192, v2, v192
	v_mul_f32_e32 v193, v3, v193
	v_cvt_pk_bf16_f32 v154, v186, v187
	v_cvt_pk_bf16_f32 v155, v188, v189
	v_cvt_pk_bf16_f32 v156, v190, v191
	v_cvt_pk_bf16_f32 v157, v192, v193
	s_nop 1
	v_permlane16_swap_b32_e32 v154, v156
	v_permlane16_swap_b32_e32 v155, v157
	global_store_dwordx4 v[184:185], v[154:157], off offset:128
	s_cbranch_vccz .LBB0_901
	s_waitcnt vmcnt(0)
	s_cmpk_gt_u32 s15, 0xff
	s_cbranch_scc1 .LBB0_912
	s_barrier
